# v34
# baseline (speedup 1.0000x reference)
.LBB0_193:
	ds_read_b128 v[64:67], v180 offset:49152
	ds_read_b128 v[68:71], v180 offset:53248
	ds_read_b128 v[128:131], v179 offset:49152
	ds_read_b128 v[132:135], v179 offset:53248
	ds_read_b128 v[248:251], v165 offset:49152
	ds_read_b128 v[252:255], v165 offset:53248
	v_exp_f32_e32 v136, v144
	v_exp_f32_e32 v137, v145
	s_waitcnt lgkmcnt(5)
	v_mfma_f32_32x32x16_bf16 v[80:95], v[64:67], v[124:127], 0
	v_exp_f32_e32 v138, v158
	v_exp_f32_e32 v139, v159
	v_exp_f32_e32 v140, v152
	v_exp_f32_e32 v141, v153
	s_waitcnt lgkmcnt(4)
	v_mfma_f32_32x32x16_bf16 v[64:79], v[68:71], v[124:127], 0
	v_exp_f32_e32 v142, v146
	v_exp_f32_e32 v143, v147
	v_add_f32_e32 v144, v216, v219
	v_add_f32_e32 v145, v213, v217
	v_add_f32_e32 v158, v212, v214
	s_waitcnt lgkmcnt(3)
	v_mfma_f32_32x32x16_bf16 v[80:95], v[128:131], v[120:123], v[80:95]
	v_add_f32_e32 v159, v210, v211
	v_add_f32_e32 v152, v207, v209
	v_add_f32_e32 v153, v206, v208
	v_add_f32_e32 v146, v195, v197
	v_add_f32_e32 v147, v194, v196
	s_waitcnt lgkmcnt(2)
	v_mfma_f32_32x32x16_bf16 v[64:79], v[132:135], v[120:123], v[64:79]
	v_add_f32_e32 v144, v144, v145
	v_add_f32_e32 v158, v158, v159
	v_add_f32_e32 v152, v152, v153
	v_add_f32_e32 v146, v146, v147
	v_add_f32_e32 v144, v144, v158
	v_add_f32_e32 v152, v152, v146
	v_add_f32_e32 v144, v144, v152
	ds_read_b128 v[128:131], v163 offset:49152
	ds_read_b128 v[132:135], v163 offset:53248
	s_sub_i32 s0, s26, 63
	s_waitcnt lgkmcnt(3)
	v_mfma_f32_32x32x16_bf16 v[80:95], v[248:251], v[116:119], v[80:95]
	s_waitcnt lgkmcnt(2)
	v_mfma_f32_32x32x16_bf16 v[64:79], v[252:255], v[116:119], v[64:79]
	ds_read_b128 v[248:251], v180 offset:57344
	ds_read_b128 v[252:255], v180 offset:61440
	s_waitcnt lgkmcnt(3)
	v_mfma_f32_32x32x16_bf16 v[80:95], v[128:131], v[112:115], v[80:95]
	s_waitcnt lgkmcnt(2)
	v_mfma_f32_32x32x16_bf16 v[64:79], v[132:135], v[112:115], v[64:79]
	ds_read_b128 v[128:131], v179 offset:57344
	ds_read_b128 v[132:135], v179 offset:61440
	s_waitcnt lgkmcnt(3)
	v_mfma_f32_32x32x16_bf16 v[80:95], v[248:251], v[108:111], v[80:95]
	s_waitcnt lgkmcnt(2)
	v_mfma_f32_32x32x16_bf16 v[64:79], v[252:255], v[108:111], v[64:79]
	ds_read_b128 v[248:251], v165 offset:57344
	ds_read_b128 v[252:255], v165 offset:61440
	s_waitcnt lgkmcnt(3)
	v_mfma_f32_32x32x16_bf16 v[80:95], v[128:131], v[104:107], v[80:95]
	s_waitcnt lgkmcnt(2)
	v_mfma_f32_32x32x16_bf16 v[64:79], v[132:135], v[104:107], v[64:79]
	ds_read_b128 v[128:131], v163 offset:57344
	ds_read_b128 v[132:135], v163 offset:61440
	s_waitcnt lgkmcnt(3)
	v_mfma_f32_32x32x16_bf16 v[80:95], v[248:251], v[100:103], v[80:95]
	s_waitcnt lgkmcnt(2)
	v_mfma_f32_32x32x16_bf16 v[64:79], v[252:255], v[100:103], v[64:79]
	s_waitcnt lgkmcnt(1)
	v_mfma_f32_32x32x16_bf16 v[80:95], v[128:131], v[96:99], v[80:95]
	v_exp_f32_e32 v128, v156
	v_exp_f32_e32 v129, v157
	v_exp_f32_e32 v130, v154
	v_exp_f32_e32 v131, v155
	s_waitcnt lgkmcnt(0)
	v_mfma_f32_32x32x16_bf16 v[64:79], v[132:135], v[96:99], v[64:79]
	v_exp_f32_e32 v132, v150
	v_exp_f32_e32 v133, v151
	v_exp_f32_e32 v134, v148
	v_exp_f32_e32 v135, v149
	v_add_f32_e32 v145, v136, v137
	v_add_f32_e32 v158, v138, v139
	v_add_f32_e32 v159, v140, v141
	v_add_f32_e32 v152, v142, v143
	v_add_f32_e32 v153, v128, v129
	v_add_f32_e32 v146, v130, v131
	v_add_f32_e32 v147, v132, v133
	v_add_f32_e32 v248, v134, v135
	v_add_f32_e32 v145, v145, v158
	v_add_f32_e32 v159, v159, v152
	v_add_f32_e32 v153, v153, v146
	v_add_f32_e32 v147, v147, v248
	v_add_f32_e32 v145, v145, v159
	v_add_f32_e32 v153, v153, v147
	v_add_f32_e32 v145, v145, v153
	v_add_f32_e32 v190, v144, v145
	v_mov_b32_e32 v191, v190
	s_nop 1
	v_permlane32_swap_b32_e32 v190, v191
	s_nop 0
	v_cvt_pk_bf16_f32 v144, v216, v219
	s_nop 0
	v_cvt_pk_bf16_f32 v145, v213, v217
	s_nop 0
	v_cvt_pk_bf16_f32 v146, v212, v214
	s_nop 0
	v_cvt_pk_bf16_f32 v147, v210, v211
	s_nop 0
	v_cvt_pk_bf16_f32 v148, v207, v209
	s_nop 0
	v_cvt_pk_bf16_f32 v149, v206, v208
	s_nop 0
	v_cvt_pk_bf16_f32 v150, v195, v197
	s_nop 0
	v_cvt_pk_bf16_f32 v151, v194, v196
	s_nop 0
	v_cvt_pk_bf16_f32 v152, v128, v129
	s_nop 0
	v_cvt_pk_bf16_f32 v153, v130, v131
	s_nop 0
	v_cvt_pk_bf16_f32 v154, v132, v133
	s_nop 0
	v_cvt_pk_bf16_f32 v155, v134, v135
	s_nop 0
	v_cvt_pk_bf16_f32 v156, v136, v137
	s_nop 0
	v_cvt_pk_bf16_f32 v157, v138, v139
	s_nop 0
	v_cvt_pk_bf16_f32 v158, v140, v141
	s_nop 0
	v_cvt_pk_bf16_f32 v159, v142, v143
	s_nop 0
	v_permlane32_swap_b32_e32 v144, v146
	v_permlane32_swap_b32_e32 v145, v147
	v_permlane32_swap_b32_e32 v148, v150
	v_permlane32_swap_b32_e32 v149, v151
	v_permlane32_swap_b32_e32 v152, v154
	v_permlane32_swap_b32_e32 v153, v155
	v_permlane32_swap_b32_e32 v156, v158
	v_permlane32_swap_b32_e32 v157, v159
	v_add_u32_e32 v192, s26, v160
	v_add_u32_e32 v128, 1, v192
	v_add_u32_e32 v130, 33, v192
	v_ashrrev_i32_e32 v129, 31, v128
	v_ashrrev_i32_e32 v131, 31, v130
	v_lshlrev_b64 v[136:137], 8, v[128:129]
	v_lshlrev_b64 v[138:139], 8, v[130:131]
	v_lshl_add_u64 v[128:129], v[166:167], 0, v[136:137]
	v_lshl_add_u64 v[132:133], v[166:167], 0, v[138:139]
	v_lshl_add_u64 v[136:137], v[168:169], 0, v[136:137]
	v_lshl_add_u64 v[140:141], v[168:169], 0, v[138:139]
	global_load_dwordx4 v[128:131], v[128:129], off
	s_nop 0
	global_load_dwordx4 v[132:135], v[132:133], off
	s_nop 0
	global_load_dwordx4 v[136:139], v[136:137], off
	s_nop 0
	global_load_dwordx4 v[140:143], v[140:141], off
	ds_read_b64_tr_b16 v[194:195], v173 offset:0
	ds_read_b64_tr_b16 v[196:197], v173 offset:0x800
	ds_read_b64_tr_b16 v[206:207], v173 offset:0x1000
	ds_read_b64_tr_b16 v[208:209], v173 offset:0x1800
	ds_read_b64_tr_b16 v[210:211], v173 offset:0x2000
	ds_read_b64_tr_b16 v[212:213], v173 offset:0x2800
	ds_read_b64_tr_b16 v[214:215], v173 offset:0x3000
	ds_read_b64_tr_b16 v[216:217], v173 offset:0x3800
	s_waitcnt lgkmcnt(0)
	s_nop 0
	v_mfma_f32_32x32x16_bf16 v[48:63], v[144:147], v[194:197], v[48:63]
	ds_read_b64_tr_b16 v[194:195], v173 offset:0x200
	ds_read_b64_tr_b16 v[196:197], v173 offset:0xa00
	v_mfma_f32_32x32x16_bf16 v[48:63], v[148:151], v[206:209], v[48:63]
	ds_read_b64_tr_b16 v[206:207], v173 offset:0x1200
	ds_read_b64_tr_b16 v[208:209], v173 offset:0x1a00
	v_mfma_f32_32x32x16_bf16 v[48:63], v[152:155], v[210:213], v[48:63]
	ds_read_b64_tr_b16 v[210:211], v173 offset:0x2200
	ds_read_b64_tr_b16 v[212:213], v173 offset:0x2a00
	v_mfma_f32_32x32x16_bf16 v[48:63], v[156:159], v[214:217], v[48:63]
	ds_read_b64_tr_b16 v[214:215], v173 offset:0x3200
	ds_read_b64_tr_b16 v[216:217], v173 offset:0x3a00
	s_waitcnt lgkmcnt(0)
	v_mfma_f32_32x32x16_bf16 v[32:47], v[144:147], v[194:197], v[32:47]
	ds_read_b64_tr_b16 v[194:195], v173 offset:0x400
	ds_read_b64_tr_b16 v[196:197], v173 offset:0xc00
	v_mfma_f32_32x32x16_bf16 v[32:47], v[148:151], v[206:209], v[32:47]
	ds_read_b64_tr_b16 v[206:207], v173 offset:0x1400
	ds_read_b64_tr_b16 v[208:209], v173 offset:0x1c00
	v_mfma_f32_32x32x16_bf16 v[32:47], v[152:155], v[210:213], v[32:47]
	ds_read_b64_tr_b16 v[210:211], v173 offset:0x2400
	ds_read_b64_tr_b16 v[212:213], v173 offset:0x2c00
	v_mfma_f32_32x32x16_bf16 v[32:47], v[156:159], v[214:217], v[32:47]
	ds_read_b64_tr_b16 v[214:215], v173 offset:0x3400
	ds_read_b64_tr_b16 v[216:217], v173 offset:0x3c00
	s_waitcnt lgkmcnt(0)
	v_mfma_f32_32x32x16_bf16 v[16:31], v[144:147], v[194:197], v[16:31]
	ds_read_b64_tr_b16 v[194:195], v173 offset:0x600
	ds_read_b64_tr_b16 v[196:197], v173 offset:0xe00
	v_mfma_f32_32x32x16_bf16 v[16:31], v[148:151], v[206:209], v[16:31]
	ds_read_b64_tr_b16 v[206:207], v173 offset:0x1600
	ds_read_b64_tr_b16 v[208:209], v173 offset:0x1e00
	v_mfma_f32_32x32x16_bf16 v[16:31], v[152:155], v[210:213], v[16:31]
	ds_read_b64_tr_b16 v[210:211], v173 offset:0x2600
	ds_read_b64_tr_b16 v[212:213], v173 offset:0x2e00
	v_mfma_f32_32x32x16_bf16 v[16:31], v[156:159], v[214:217], v[16:31]
	ds_read_b64_tr_b16 v[214:215], v173 offset:0x3600
	ds_read_b64_tr_b16 v[216:217], v173 offset:0x3e00
	s_waitcnt lgkmcnt(0)
	v_mfma_f32_32x32x16_bf16 v[0:15], v[144:147], v[194:197], v[0:15]
	s_cmp_le_i32 s26, s19
	s_cselect_b64 s[2:3], -1, 0
	s_cmp_gt_i32 s0, s24
	s_cselect_b64 s[0:1], -1, 0
	s_and_b64 s[0:1], s[2:3], s[0:1]
	s_and_b64 vcc, exec, s[0:1]
	v_mfma_f32_32x32x16_bf16 v[0:15], v[148:151], v[206:209], v[0:15]
	v_mfma_f32_32x32x16_bf16 v[0:15], v[152:155], v[210:213], v[0:15]
	v_mfma_f32_32x32x16_bf16 v[0:15], v[156:159], v[214:217], v[0:15]
	s_waitcnt vmcnt(0)
	ds_write_b128 v176, v[136:139] offset:32768
	ds_write_b128 v176, v[140:143] offset:36864
	s_cbranch_vccnz .LBB0_195
	v_add_u32_e32 v144, 0x207b, v188
	v_cmp_gt_u32_e32 vcc, s73, v144
	v_add_u32_e32 v144, 0x5b, v188
	s_nop 0
	v_cndmask_b32_e32 v80, v202, v80, vcc
	v_cmp_lt_u32_e32 vcc, s95, v144
	v_add_u32_e32 v144, 0x7a, v188
	s_nop 0
	v_cndmask_b32_e32 v64, v202, v64, vcc
	v_cmp_lt_u32_e32 vcc, s95, v144
	v_add_u32_e32 v144, 0x5a, v188
	s_nop 0
	v_cndmask_b32_e32 v81, v202, v81, vcc
	v_cmp_lt_u32_e32 vcc, s95, v144
	v_add_u32_e32 v144, 0x79, v188
	s_nop 0
	v_cndmask_b32_e32 v65, v202, v65, vcc
	v_cmp_lt_u32_e32 vcc, s95, v144
	v_add_u32_e32 v144, 0x59, v188
	s_nop 0
	v_cndmask_b32_e32 v82, v202, v82, vcc
	v_cmp_lt_u32_e32 vcc, s95, v144
	v_add_u32_e32 v144, 0x78, v188
	s_nop 0
	v_cndmask_b32_e32 v66, v202, v66, vcc
	v_cmp_lt_u32_e32 vcc, s95, v144
	v_add_u32_e32 v144, 0x58, v188
	s_nop 0
	v_cndmask_b32_e32 v83, v202, v83, vcc
	v_cmp_lt_u32_e32 vcc, s95, v144
	v_add_u32_e32 v144, 0x73, v188
	s_nop 0
	v_cndmask_b32_e32 v67, v202, v67, vcc
	v_cmp_lt_u32_e32 vcc, s95, v144
	v_add_u32_e32 v144, 0x53, v188
	s_nop 0
	v_cndmask_b32_e32 v84, v202, v84, vcc
	v_cmp_lt_u32_e32 vcc, s95, v144
	v_add_u32_e32 v144, 0x72, v188
	s_nop 0
	v_cndmask_b32_e32 v68, v202, v68, vcc
	v_cmp_lt_u32_e32 vcc, s95, v144
	v_add_u32_e32 v144, 0x52, v188
	s_nop 0
	v_cndmask_b32_e32 v85, v202, v85, vcc
	v_cmp_lt_u32_e32 vcc, s95, v144
	v_add_u32_e32 v144, 0x71, v188
	s_nop 0
	v_cndmask_b32_e32 v69, v202, v69, vcc
	v_cmp_lt_u32_e32 vcc, s95, v144
	v_add_u32_e32 v144, 0x51, v188
	s_nop 0
	v_cndmask_b32_e32 v86, v202, v86, vcc
	v_cmp_lt_u32_e32 vcc, s95, v144
	v_add_u32_e32 v144, 0x70, v188
	s_nop 0
	v_cndmask_b32_e32 v70, v202, v70, vcc
	v_cmp_lt_u32_e32 vcc, s95, v144
	v_add_u32_e32 v144, 0x50, v188
	s_nop 0
	v_cndmask_b32_e32 v87, v202, v87, vcc
	v_cmp_lt_u32_e32 vcc, s95, v144
	v_add_u32_e32 v144, 0x6b, v188
	s_nop 0
	v_cndmask_b32_e32 v71, v202, v71, vcc
	v_cmp_lt_u32_e32 vcc, s95, v144
	v_add_u32_e32 v144, 0x4b, v188
	s_nop 0
	v_cndmask_b32_e32 v88, v202, v88, vcc
	v_cmp_lt_u32_e32 vcc, s95, v144
	v_add_u32_e32 v144, 0x6a, v188
	s_nop 0
	v_cndmask_b32_e32 v72, v202, v72, vcc
	v_cmp_lt_u32_e32 vcc, s95, v144
	v_add_u32_e32 v144, 0x4a, v188
	s_nop 0
	v_cndmask_b32_e32 v89, v202, v89, vcc
	v_cmp_lt_u32_e32 vcc, s95, v144
	v_add_u32_e32 v144, 0x69, v188
	s_nop 0
	v_cndmask_b32_e32 v73, v202, v73, vcc
	v_cmp_lt_u32_e32 vcc, s95, v144
	v_add_u32_e32 v144, 0x49, v188
	s_nop 0
	v_cndmask_b32_e32 v90, v202, v90, vcc
	v_cmp_lt_u32_e32 vcc, s95, v144
	v_add_u32_e32 v144, 0x68, v188
	s_nop 0
	v_cndmask_b32_e32 v74, v202, v74, vcc
	v_cmp_lt_u32_e32 vcc, s95, v144
	v_add_u32_e32 v144, 0x48, v188
	s_nop 0
	v_cndmask_b32_e32 v91, v202, v91, vcc
	v_cmp_lt_u32_e32 vcc, s95, v144
	v_add_u32_e32 v144, 0x63, v188
	s_nop 0
	v_cndmask_b32_e32 v75, v202, v75, vcc
	v_cmp_lt_u32_e32 vcc, s95, v144
	v_add_u32_e32 v144, 0x43, v188
	s_nop 0
	v_cndmask_b32_e32 v92, v202, v92, vcc
	v_cmp_lt_u32_e32 vcc, s95, v144
	v_add_u32_e32 v144, 0x62, v188
	s_nop 0
	v_cndmask_b32_e32 v76, v202, v76, vcc
	v_cmp_lt_u32_e32 vcc, s95, v144
	v_add_u32_e32 v144, 0x42, v188
	s_nop 0
	v_cndmask_b32_e32 v93, v202, v93, vcc
	v_cmp_lt_u32_e32 vcc, s95, v144
	v_add_u32_e32 v144, 0x61, v188
	s_nop 0
	v_cndmask_b32_e32 v77, v202, v77, vcc
	v_cmp_lt_u32_e32 vcc, s95, v144
	v_add_u32_e32 v144, 0x41, v188
	s_nop 0
	v_cndmask_b32_e32 v94, v202, v94, vcc
	v_cmp_lt_u32_e32 vcc, s95, v144
	v_add_u32_e32 v144, 0x60, v188
	s_nop 0
	v_cndmask_b32_e32 v78, v202, v78, vcc
	v_cmp_lt_u32_e32 vcc, s95, v144
	v_add_u32_e32 v144, 64, v188
	s_nop 0
	v_cndmask_b32_e32 v95, v202, v95, vcc
	v_cmp_lt_u32_e32 vcc, s95, v144
	s_nop 1
	v_cndmask_b32_e32 v79, v202, v79, vcc

.Lhs2_top:
	ds_read_b128 v[64:67], v180 offset:32768
	ds_read_b128 v[68:71], v180 offset:36864
	ds_read_b128 v[218:221], v179 offset:32768
	ds_read_b128 v[222:225], v179 offset:36864
	ds_read_b128 v[248:251], v165 offset:32768
	ds_read_b128 v[252:255], v165 offset:36864
	v_exp_f32_e32 v211, v211
	v_exp_f32_e32 v212, v212
	s_waitcnt lgkmcnt(5)
	v_mfma_f32_32x32x16_bf16 v[80:95], v[64:67], v[124:127], 0
	v_exp_f32_e32 v213, v213
	v_exp_f32_e32 v214, v214
	v_exp_f32_e32 v196, v196
	v_exp_f32_e32 v197, v197
	v_exp_f32_e32 v206, v206
	v_exp_f32_e32 v207, v207
	v_exp_f32_e32 v208, v208
	s_waitcnt lgkmcnt(4)
	v_mfma_f32_32x32x16_bf16 v[64:79], v[68:71], v[124:127], 0
	v_exp_f32_e32 v209, v209
	v_exp_f32_e32 v210, v210
	v_exp_f32_e32 v195, v195
	v_exp_f32_e32 v216, v216
	v_exp_f32_e32 v217, v217
	v_exp_f32_e32 v194, v194
	v_exp_f32_e32 v143, v215
	s_waitcnt lgkmcnt(3)
	v_mfma_f32_32x32x16_bf16 v[80:95], v[218:221], v[120:123], v[80:95]
	s_waitcnt lgkmcnt(2)
	v_mfma_f32_32x32x16_bf16 v[64:79], v[222:225], v[120:123], v[64:79]
	ds_read_b128 v[218:221], v163 offset:32768
	ds_read_b128 v[222:225], v163 offset:36864
	s_waitcnt lgkmcnt(3)
	v_mfma_f32_32x32x16_bf16 v[80:95], v[248:251], v[116:119], v[80:95]
	s_waitcnt lgkmcnt(2)
	v_mfma_f32_32x32x16_bf16 v[64:79], v[252:255], v[116:119], v[64:79]
	ds_read_b128 v[248:251], v180 offset:40960
	ds_read_b128 v[252:255], v180 offset:45056
	s_waitcnt lgkmcnt(3)
	v_mfma_f32_32x32x16_bf16 v[80:95], v[218:221], v[112:115], v[80:95]
	s_waitcnt lgkmcnt(2)
	v_mfma_f32_32x32x16_bf16 v[64:79], v[222:225], v[112:115], v[64:79]
	ds_read_b128 v[218:221], v179 offset:40960
	ds_read_b128 v[222:225], v179 offset:45056
	s_waitcnt lgkmcnt(3)
	v_mfma_f32_32x32x16_bf16 v[80:95], v[248:251], v[108:111], v[80:95]
	s_waitcnt lgkmcnt(2)
	v_mfma_f32_32x32x16_bf16 v[64:79], v[252:255], v[108:111], v[64:79]
	ds_read_b128 v[248:251], v165 offset:40960
	ds_read_b128 v[252:255], v165 offset:45056
	s_waitcnt lgkmcnt(3)
	v_mfma_f32_32x32x16_bf16 v[80:95], v[218:221], v[104:107], v[80:95]
	s_waitcnt lgkmcnt(2)
	v_mfma_f32_32x32x16_bf16 v[64:79], v[222:225], v[104:107], v[64:79]
	ds_read_b128 v[218:221], v163 offset:40960
	ds_read_b128 v[222:225], v163 offset:45056
	s_waitcnt lgkmcnt(3)
	v_mfma_f32_32x32x16_bf16 v[80:95], v[248:251], v[100:103], v[80:95]
	s_waitcnt lgkmcnt(2)
	v_mfma_f32_32x32x16_bf16 v[64:79], v[252:255], v[100:103], v[64:79]
	s_waitcnt lgkmcnt(1)
	v_mfma_f32_32x32x16_bf16 v[80:95], v[218:221], v[96:99], v[80:95]
	s_waitcnt lgkmcnt(0)
	v_mfma_f32_32x32x16_bf16 v[64:79], v[222:225], v[96:99], v[64:79]
	v_add_f32_e32 v128, v144, v159
	v_add_f32_e32 v129, v145, v158
	v_add_f32_e32 v130, v146, v157
	v_add_f32_e32 v131, v147, v156
	v_add_f32_e32 v132, v148, v155
	v_add_f32_e32 v133, v149, v154
	v_add_f32_e32 v134, v150, v153
	v_add_f32_e32 v135, v151, v152
	v_add_f32_e32 v136, v211, v212
	v_add_f32_e32 v137, v213, v214
	v_add_f32_e32 v138, v196, v197
	v_add_f32_e32 v139, v206, v207
	v_add_f32_e32 v140, v208, v209
	v_add_f32_e32 v141, v210, v195
	v_add_f32_e32 v142, v216, v217
	v_add_f32_e32 v248, v194, v143
	v_add_f32_e32 v128, v128, v129
	v_add_f32_e32 v130, v130, v131
	v_add_f32_e32 v132, v132, v133
	v_add_f32_e32 v134, v134, v135
	v_add_f32_e32 v136, v136, v137
	v_add_f32_e32 v138, v138, v139
	v_add_f32_e32 v140, v140, v141
	v_add_f32_e32 v142, v142, v248
	v_add_f32_e32 v128, v128, v130
	v_add_f32_e32 v132, v132, v134
	v_add_f32_e32 v136, v136, v138
	v_add_f32_e32 v140, v140, v142
	v_add_f32_e32 v128, v128, v132
	v_add_f32_e32 v136, v136, v140
	v_add_f32_e32 v215, v128, v136
	v_mov_b32_e32 v218, v215
	s_nop 0
	v_cvt_pk_bf16_f32 v144, v144, v159
	s_nop 0
	v_cvt_pk_bf16_f32 v145, v145, v158
	s_nop 0
	v_cvt_pk_bf16_f32 v146, v146, v157
	s_nop 0
	v_cvt_pk_bf16_f32 v147, v147, v156
	s_nop 0
	v_cvt_pk_bf16_f32 v148, v148, v155
	s_nop 0
	v_cvt_pk_bf16_f32 v149, v149, v154
	s_nop 0
	v_cvt_pk_bf16_f32 v150, v150, v153
	s_nop 0
	v_cvt_pk_bf16_f32 v151, v151, v152
	s_nop 0
	v_cvt_pk_bf16_f32 v152, v211, v212
	s_nop 0
	v_cvt_pk_bf16_f32 v153, v213, v214
	s_nop 0
	v_cvt_pk_bf16_f32 v154, v143, v196
	s_nop 0
	v_cvt_pk_bf16_f32 v155, v197, v206
	s_nop 0
	v_cvt_pk_bf16_f32 v156, v207, v208
	s_nop 0
	v_cvt_pk_bf16_f32 v157, v209, v210
	s_nop 0
	v_cvt_pk_bf16_f32 v158, v195, v216
	s_nop 0
	v_cvt_pk_bf16_f32 v159, v217, v194
	s_nop 1
	v_permlane32_swap_b32_e32 v215, v218
	v_permlane32_swap_b32_e32 v144, v146
	v_permlane32_swap_b32_e32 v145, v147
	v_permlane32_swap_b32_e32 v148, v150
	v_permlane32_swap_b32_e32 v149, v151
	v_permlane32_swap_b32_e32 v152, v154
	v_permlane32_swap_b32_e32 v153, v155
	v_permlane32_swap_b32_e32 v156, v158
	v_permlane32_swap_b32_e32 v157, v159
	s_add_i32 s0, s25, 1
	s_cmp_lt_u32 s0, s23
	s_cselect_b64 s[2:3], -1, 0
	s_cmp_ge_u32 s0, s23
	s_cbranch_scc1 .LBB0_201
	v_add_u32_e32 v128, 0x41, v192
	v_add_u32_e32 v130, 0x61, v192
	v_ashrrev_i32_e32 v129, 31, v128
	v_ashrrev_i32_e32 v131, 31, v130
	v_lshlrev_b64 v[136:137], 8, v[128:129]
	v_lshlrev_b64 v[138:139], 8, v[130:131]
	v_lshl_add_u64 v[128:129], v[166:167], 0, v[136:137]
	v_lshl_add_u64 v[132:133], v[166:167], 0, v[138:139]
	v_lshl_add_u64 v[136:137], v[168:169], 0, v[136:137]
	v_lshl_add_u64 v[140:141], v[168:169], 0, v[138:139]
	global_load_dwordx4 v[128:131], v[128:129], off
	s_nop 0
	global_load_dwordx4 v[132:135], v[132:133], off
	s_nop 0
	global_load_dwordx4 v[136:139], v[136:137], off
	s_nop 0
	global_load_dwordx4 v[140:143], v[140:141], off
